# filter finalize: 8 H-row loads per item issued together with the hsum loads
# baseline (speedup 1.0000x reference)
.LBB0_238:
	s_lshr_b32 s11, s27, 2
	v_cvt_f32_u32_e32 v2, s11
	s_sub_i32 s15, 0, s11
	s_abs_i32 s14, s4
	s_ashr_i32 s9, s4, 31
	v_rcp_iflag_f32_e32 v2, v2
	s_mov_b64 s[12:13], s[0:1]
	s_load_dwordx2 s[12:13], s[12:13], 0x128
	v_mul_f32_e32 v2, 0x4f7ffffe, v2
	v_cvt_u32_f32_e32 v2, v2
	s_nop 0
	v_readfirstlane_b32 s20, v2
	s_mul_i32 s15, s15, s20
	s_mul_hi_u32 s15, s20, s15
	s_add_i32 s20, s20, s15
	s_mul_hi_u32 s15, s14, s20
	s_mul_i32 s20, s15, s11
	s_sub_i32 s14, s14, s20
	s_add_i32 s21, s15, 1
	s_sub_i32 s20, s14, s11
	s_cmp_ge_u32 s14, s11
	s_cselect_b32 s15, s21, s15
	s_cselect_b32 s14, s20, s14
	s_add_i32 s20, s15, 1
	s_cmp_ge_u32 s14, s11
	s_cselect_b32 s14, s20, s15
	s_xor_b32 s14, s14, s9
	s_sub_i32 s9, s14, s9
	s_mul_i32 s11, s9, s11
	s_lshl_b32 s8, s8, 2
	s_sub_i32 s4, s4, s11
	s_waitcnt lgkmcnt(0)
	s_add_u32 s20, s12, s8
	s_addc_u32 s21, s13, 0
	s_lshl_b32 s14, s9, 10
	s_add_i32 s8, s14, s10
	v_add_u32_e32 v2, s8, v0
	v_ashrrev_i32_e32 v3, 31, v2
	v_lshl_add_u64 v[4:5], v[2:3], 2, s[34:35]
	v_add_u32_e32 v2, 0x200, v2
	s_mov_b64 s[12:13], s[0:1]
	v_ashrrev_i32_e32 v3, 31, v2
	v_lshl_add_u64 v[2:3], v[2:3], 2, s[34:35]
	global_load_dword v6, v[4:5], off
	global_load_dword v7, v[2:3], off
	s_ashr_i32 s15, s14, 31
	s_lshl_b64 s[10:11], s[14:15], 2
	s_lshl_b32 s8, s4, 3
	s_sub_i32 s28, 0, s27
	s_add_u32 s4, s20, s10
	s_addc_u32 s11, s21, s11
	s_add_u32 s10, s4, 0xa990100
	s_addc_u32 s11, s11, 0
	s_not_b32 s4, s8
	s_add_i32 s4, s27, s4
	s_cmp_lt_i32 s4, 0
	v_lshlrev_b32_e32 v13, 2, v0
	v_mov_b32_e32 v200, 0
	v_mov_b32_e32 v201, 0
	v_mov_b32_e32 v202, 0
	v_mov_b32_e32 v203, 0
	v_mov_b32_e32 v204, 0
	v_mov_b32_e32 v205, 0
	v_mov_b32_e32 v206, 0
	v_mov_b32_e32 v207, 0
	s_xor_b32 s4, s8, -1
	s_add_i32 s14, s27, s4
	s_cmp_gt_i32 s14, -1
	s_cbranch_scc1 .Lff_a0
	s_cmp_le_u32 s14, s28
	s_cbranch_scc1 .Lff_n0
	s_or_b32 s4, s8, 0
	s_sub_i32 s4, s4, s27
	s_lshl_b32 s4, s4, 13
	s_addk_i32 s4, 0x800
	s_branch .Lff_l0
.Lff_a0:
	s_lshl_b32 s4, s14, 13
.Lff_l0:
	s_add_u32 s14, s10, s4
	s_addc_u32 s15, s11, 0
	global_load_dword v200, v13, s[14:15]
.Lff_n0:
	s_xor_b32 s4, s8, -2
	s_add_i32 s14, s27, s4
	s_cmp_gt_i32 s14, -1
	s_cbranch_scc1 .Lff_a1
	s_cmp_le_u32 s14, s28
	s_cbranch_scc1 .Lff_n1
	s_or_b32 s4, s8, 1
	s_sub_i32 s4, s4, s27
	s_lshl_b32 s4, s4, 13
	s_addk_i32 s4, 0x800
	s_branch .Lff_l1

.Lff_l1:
	s_add_u32 s14, s10, s4
	s_addc_u32 s15, s11, 0
	global_load_dword v201, v13, s[14:15]
.Lff_n1:
	s_xor_b32 s4, s8, -3
	s_add_i32 s14, s27, s4
	s_cmp_gt_i32 s14, -1
	s_cbranch_scc1 .Lff_a2
	s_cmp_le_u32 s14, s28
	s_cbranch_scc1 .Lff_n2
	s_or_b32 s4, s8, 2
	s_sub_i32 s4, s4, s27
	s_lshl_b32 s4, s4, 13
	s_addk_i32 s4, 0x800
	s_branch .Lff_l2

.Lff_l2:
	s_add_u32 s14, s10, s4
	s_addc_u32 s15, s11, 0
	global_load_dword v202, v13, s[14:15]
.Lff_n2:
	s_xor_b32 s4, s8, -4
	s_add_i32 s14, s27, s4
	s_cmp_gt_i32 s14, -1
	s_cbranch_scc1 .Lff_a3
	s_cmp_le_u32 s14, s28
	s_cbranch_scc1 .Lff_n3
	s_or_b32 s4, s8, 3
	s_sub_i32 s4, s4, s27
	s_lshl_b32 s4, s4, 13
	s_addk_i32 s4, 0x800
	s_branch .Lff_l3

.Lff_l3:
	s_add_u32 s14, s10, s4
	s_addc_u32 s15, s11, 0
	global_load_dword v203, v13, s[14:15]
.Lff_n3:
	s_xor_b32 s4, s8, -5
	s_add_i32 s14, s27, s4
	s_cmp_gt_i32 s14, -1
	s_cbranch_scc1 .Lff_a4
	s_cmp_le_u32 s14, s28
	s_cbranch_scc1 .Lff_n4
	s_or_b32 s4, s8, 4
	s_sub_i32 s4, s4, s27
	s_lshl_b32 s4, s4, 13
	s_addk_i32 s4, 0x800
	s_branch .Lff_l4

.Lff_l4:
	s_add_u32 s14, s10, s4
	s_addc_u32 s15, s11, 0
	global_load_dword v204, v13, s[14:15]
.Lff_n4:
	s_xor_b32 s4, s8, -6
	s_add_i32 s14, s27, s4
	s_cmp_gt_i32 s14, -1
	s_cbranch_scc1 .Lff_a5
	s_cmp_le_u32 s14, s28
	s_cbranch_scc1 .Lff_n5
	s_or_b32 s4, s8, 5
	s_sub_i32 s4, s4, s27
	s_lshl_b32 s4, s4, 13
	s_addk_i32 s4, 0x800
	s_branch .Lff_l5

.Lff_l5:
	s_add_u32 s14, s10, s4
	s_addc_u32 s15, s11, 0
	global_load_dword v205, v13, s[14:15]
.Lff_n5:
	s_xor_b32 s4, s8, -7
	s_add_i32 s14, s27, s4
	s_cmp_gt_i32 s14, -1
	s_cbranch_scc1 .Lff_a6
	s_cmp_le_u32 s14, s28
	s_cbranch_scc1 .Lff_n6
	s_or_b32 s4, s8, 6
	s_sub_i32 s4, s4, s27
	s_lshl_b32 s4, s4, 13
	s_addk_i32 s4, 0x800
	s_branch .Lff_l6

.Lff_l6:
	s_add_u32 s14, s10, s4
	s_addc_u32 s15, s11, 0
	global_load_dword v206, v13, s[14:15]
.Lff_n6:
	s_xor_b32 s4, s8, -8
	s_add_i32 s14, s27, s4
	s_cmp_gt_i32 s14, -1
	s_cbranch_scc1 .Lff_a7
	s_cmp_le_u32 s14, s28
	s_cbranch_scc1 .Lff_n7
	s_or_b32 s4, s8, 7
	s_sub_i32 s4, s4, s27
	s_lshl_b32 s4, s4, 13
	s_addk_i32 s4, 0x800
	s_branch .Lff_l7

.Lff_l7:
	s_add_u32 s14, s10, s4
	s_addc_u32 s15, s11, 0
	global_load_dword v207, v13, s[14:15]
.Lff_n7:
	s_waitcnt vmcnt(0)
	v_add_f32_e32 v2, v6, v7
	v_div_scale_f32 v3, s[14:15], v2, v2, 1.0
	v_rcp_f32_e32 v4, v3
	v_div_scale_f32 v5, vcc, 1.0, v2, 1.0
	s_mov_b64 s[14:15], -1
	v_fma_f32 v6, -v3, v4, 1.0
	v_fmac_f32_e32 v4, v6, v4
	v_mul_f32_e32 v6, v5, v4
	v_fma_f32 v7, -v3, v6, v5
	v_fmac_f32_e32 v6, v7, v4
	v_fma_f32 v3, -v3, v6, v5
	v_div_fmas_f32 v3, v3, v4, v6
	v_div_fixup_f32 v4, v3, v2, 1.0
	v_mul_f32_e32 v5, v4, v200
	v_mul_f32_e32 v6, v4, v201
	v_mul_f32_e32 v7, v4, v202
	v_mul_f32_e32 v8, v4, v203
	v_mul_f32_e32 v9, v4, v204
	v_mul_f32_e32 v10, v4, v205
	v_mul_f32_e32 v11, v4, v206
	v_mul_f32_e32 v12, v4, v207
	s_load_dwordx2 s[12:13], s[12:13], 0x128
	s_branch .LBB0_230
